# elementwise phase: conv_dw to LDS copy issues its 16 loads together (was a serialized load+wait per element)
# speedup vs baseline: 1.0554x; 1.0052x over previous
.LBB0_292:
	s_and_b64 vcc, exec, s[0:1]
	s_cbranch_vccz .LBB0_527
	s_cmp_gt_i32 s58, 2
	s_mov_b64 s[0:1], -1
	s_cbranch_scc0 .LBB0_523
	s_add_u32 s42, s48, 0xa600000
	s_addc_u32 s43, s49, 0
	s_add_u32 s68, s48, 0xe600000
	s_addc_u32 s69, s49, 0
	s_add_u32 s70, s48, 0xf600000
	s_addc_u32 s71, s49, 0
	s_cmp_lt_i32 s58, 4
	s_cbranch_scc1 .LBB0_493
	s_cmp_gt_i32 s58, 4
	s_cbranch_scc0 .LBB0_409
	s_movk_i32 s0, 0x1f00
	v_cmp_gt_i32_e32 vcc, s0, v198
	s_and_saveexec_b64 s[0:1], vcc
	s_cbranch_execz .LBB0_299
	v_readlane_b32 s4, v255, 16
	v_mov_b32_e32 v4, 0x20480
	ds_read2_b32 v[4:5], v4 offset1:1
	s_mul_i32 s2, s4, 0x7c00
	v_lshl_add_u32 v0, v198, 2, s2
	v_lshlrev_b32_e32 v3, 2, v198
	v_add_u32_e32 v41, 0x800, v0
	v_add_u32_e32 v42, 0x1000, v0
	v_add_u32_e32 v43, 0x1800, v0
	v_add_u32_e32 v44, 0x2000, v0
	v_add_u32_e32 v45, 0x2800, v0
	v_add_u32_e32 v46, 0x3000, v0
	v_add_u32_e32 v47, 0x3800, v0
	v_add_u32_e32 v48, 0x4000, v0
	v_add_u32_e32 v49, 0x4800, v0
	v_add_u32_e32 v50, 0x5000, v0
	v_add_u32_e32 v51, 0x5800, v0
	v_add_u32_e32 v52, 0x6000, v0
	v_add_u32_e32 v53, 0x6800, v0
	v_add_u32_e32 v54, 0x7000, v0
	v_add_u32_e32 v55, 0x7800, v0
	s_waitcnt lgkmcnt(0)
	v_readfirstlane_b32 s6, v4
	v_readfirstlane_b32 s7, v5
	s_nop 4
	global_load_dword v20, v0, s[6:7]
	global_load_dword v21, v41, s[6:7]
	global_load_dword v22, v42, s[6:7]
	global_load_dword v23, v43, s[6:7]
	global_load_dword v24, v44, s[6:7]
	global_load_dword v25, v45, s[6:7]
	global_load_dword v26, v46, s[6:7]
	global_load_dword v27, v47, s[6:7]
	global_load_dword v28, v48, s[6:7]
	global_load_dword v29, v49, s[6:7]
	global_load_dword v30, v50, s[6:7]
	global_load_dword v31, v51, s[6:7]
	global_load_dword v32, v52, s[6:7]
	global_load_dword v33, v53, s[6:7]
	global_load_dword v34, v54, s[6:7]
	v_cmp_gt_u32_e32 vcc, 0x100, v198
	s_and_saveexec_b64 s[4:5], vcc
	global_load_dword v35, v55, s[6:7]
	s_or_b64 exec, exec, s[4:5]
	s_waitcnt vmcnt(0)
	ds_write_b32 v3, v20
	ds_write_b32 v3, v21 offset:2048
	ds_write_b32 v3, v22 offset:4096
	ds_write_b32 v3, v23 offset:6144
	ds_write_b32 v3, v24 offset:8192
	ds_write_b32 v3, v25 offset:10240
	ds_write_b32 v3, v26 offset:12288
	ds_write_b32 v3, v27 offset:14336
	ds_write_b32 v3, v28 offset:16384
	ds_write_b32 v3, v29 offset:18432
	ds_write_b32 v3, v30 offset:20480
	ds_write_b32 v3, v31 offset:22528
	ds_write_b32 v3, v32 offset:24576
	ds_write_b32 v3, v33 offset:26624
	ds_write_b32 v3, v34 offset:28672
	s_and_saveexec_b64 s[4:5], vcc
	ds_write_b32 v3, v35 offset:30720
	s_or_b64 exec, exec, s[4:5]
